# accumulator zeroing between GEMM units with 64-bit moves
# baseline (speedup 1.0000x reference)
; template <int NT, class Epi>
; __device__ __forceinline__ void gemm_phase(LAS unsigned char* lds, const int K, const Sched& S, const Epi& E, const int wave_s) {
;     ...
;         const bool keep = E(acc, cur, wr, wc, fr, fq);
;         __builtin_amdgcn_s_waitcnt(0x0F70);
;         if (!has_next) break;
;         if (!keep) {
; #pragma unroll
;             for (int a = 0; a < 2; ++a)
; #pragma unroll
;                 for (int b = 0; b < 2; ++b)
; #pragma unroll
;                     for (int m = 0; m < 4; ++m)
; #pragma unroll
;                         for (int n = 0; n < 2; ++n) acc[a][b][m][n] = (f32x4){0.f, 0.f, 0.f, 0.f};
;         }
;         cur = nxt; cA = nA; cB = nB; ++ui;
.LBB0_44:
	s_add_u32 s88, s24, 0x100
	v_mov_b32_e32 v0, 0
	s_addc_u32 s90, s25, 0
	s_mov_b32 s91, -2
	v_mov_b64_e32 v[0:1], 0
	v_mov_b64_e32 v[2:3], 0
	v_mov_b64_e32 v[4:5], 0
	v_mov_b64_e32 v[6:7], 0
	v_mov_b64_e32 v[8:9], 0
	v_mov_b64_e32 v[10:11], 0
	v_mov_b64_e32 v[12:13], 0
	v_mov_b64_e32 v[14:15], 0
	v_mov_b64_e32 v[16:17], 0
	v_mov_b64_e32 v[18:19], 0
	v_mov_b64_e32 v[20:21], 0
	v_mov_b64_e32 v[22:23], 0
	v_mov_b64_e32 v[24:25], 0
	v_mov_b64_e32 v[26:27], 0
	v_mov_b64_e32 v[28:29], 0
	v_mov_b64_e32 v[30:31], 0
	v_mov_b64_e32 v[32:33], 0
	v_mov_b64_e32 v[34:35], 0
	v_mov_b64_e32 v[36:37], 0
	v_mov_b64_e32 v[38:39], 0
	v_mov_b64_e32 v[40:41], 0
	v_mov_b64_e32 v[42:43], 0
	v_mov_b64_e32 v[44:45], 0
	v_mov_b64_e32 v[46:47], 0
	v_mov_b64_e32 v[48:49], 0
	v_mov_b64_e32 v[50:51], 0
	v_mov_b64_e32 v[52:53], 0
	v_mov_b64_e32 v[54:55], 0
	v_mov_b64_e32 v[56:57], 0
	v_mov_b64_e32 v[58:59], 0
	v_mov_b64_e32 v[60:61], 0
	v_mov_b64_e32 v[62:63], 0
	v_mov_b64_e32 v[64:65], 0
	v_mov_b64_e32 v[66:67], 0
	v_mov_b64_e32 v[68:69], 0
	v_mov_b64_e32 v[70:71], 0
	v_mov_b64_e32 v[72:73], 0
	v_mov_b64_e32 v[74:75], 0
	v_mov_b64_e32 v[76:77], 0
	v_mov_b64_e32 v[78:79], 0
	v_mov_b64_e32 v[80:81], 0
	v_mov_b64_e32 v[82:83], 0
	v_mov_b64_e32 v[84:85], 0
	v_mov_b64_e32 v[86:87], 0
	v_mov_b64_e32 v[88:89], 0
	v_mov_b64_e32 v[90:91], 0
	v_mov_b64_e32 v[92:93], 0
	v_mov_b64_e32 v[94:95], 0
	v_mov_b64_e32 v[96:97], 0
	v_mov_b64_e32 v[98:99], 0
	v_mov_b64_e32 v[100:101], 0
	v_mov_b64_e32 v[102:103], 0
	v_mov_b64_e32 v[104:105], 0
	v_mov_b64_e32 v[106:107], 0
	v_mov_b64_e32 v[108:109], 0
	v_mov_b64_e32 v[110:111], 0
	v_mov_b64_e32 v[112:113], 0
	v_mov_b64_e32 v[114:115], 0
	v_mov_b64_e32 v[116:117], 0
	v_mov_b64_e32 v[118:119], 0
	v_mov_b64_e32 v[120:121], 0
	v_mov_b64_e32 v[122:123], 0
	v_mov_b64_e32 v[124:125], 0
	v_mov_b64_e32 v[126:127], 0

; template <int NT, class Epi>
; __device__ __forceinline__ void gemm_phase(LAS unsigned char* lds, const int K, const Sched& S, const Epi& E, const int wave_s) {
;     ...
;         const bool keep = E(acc, cur, wr, wc, fr, fq);
;         __builtin_amdgcn_s_waitcnt(0x0F70);
;         if (!has_next) break;
;         if (!keep) {
; #pragma unroll
;             for (int a = 0; a < 2; ++a)
; #pragma unroll
;                 for (int b = 0; b < 2; ++b)
; #pragma unroll
;                     for (int m = 0; m < 4; ++m)
; #pragma unroll
;                         for (int n = 0; n < 2; ++n) acc[a][b][m][n] = (f32x4){0.f, 0.f, 0.f, 0.f};
;         }
;         cur = nxt; cA = nA; cB = nB; ++ui;
.LBB0_68:
	s_add_u32 s96, s26, 0x100
	v_mov_b32_e32 v0, 0
	s_addc_u32 s97, s27, 0
	s_mov_b32 vcc_lo, -2
	v_mov_b64_e32 v[0:1], 0
	v_mov_b64_e32 v[2:3], 0
	v_mov_b64_e32 v[4:5], 0
	v_mov_b64_e32 v[6:7], 0
	v_mov_b64_e32 v[8:9], 0
	v_mov_b64_e32 v[10:11], 0
	v_mov_b64_e32 v[12:13], 0
	v_mov_b64_e32 v[14:15], 0
	v_mov_b64_e32 v[16:17], 0
	v_mov_b64_e32 v[18:19], 0
	v_mov_b64_e32 v[20:21], 0
	v_mov_b64_e32 v[22:23], 0
	v_mov_b64_e32 v[24:25], 0
	v_mov_b64_e32 v[26:27], 0
	v_mov_b64_e32 v[28:29], 0
	v_mov_b64_e32 v[30:31], 0
	v_mov_b64_e32 v[32:33], 0
	v_mov_b64_e32 v[34:35], 0
	v_mov_b64_e32 v[36:37], 0
	v_mov_b64_e32 v[38:39], 0
	v_mov_b64_e32 v[40:41], 0
	v_mov_b64_e32 v[42:43], 0
	v_mov_b64_e32 v[44:45], 0
	v_mov_b64_e32 v[46:47], 0
	v_mov_b64_e32 v[48:49], 0
	v_mov_b64_e32 v[50:51], 0
	v_mov_b64_e32 v[52:53], 0
	v_mov_b64_e32 v[54:55], 0
	v_mov_b64_e32 v[56:57], 0
	v_mov_b64_e32 v[58:59], 0
	v_mov_b64_e32 v[60:61], 0
	v_mov_b64_e32 v[62:63], 0
	v_mov_b64_e32 v[64:65], 0
	v_mov_b64_e32 v[66:67], 0
	v_mov_b64_e32 v[68:69], 0
	v_mov_b64_e32 v[70:71], 0
	v_mov_b64_e32 v[72:73], 0
	v_mov_b64_e32 v[74:75], 0
	v_mov_b64_e32 v[76:77], 0
	v_mov_b64_e32 v[78:79], 0
	v_mov_b64_e32 v[80:81], 0
	v_mov_b64_e32 v[82:83], 0
	v_mov_b64_e32 v[84:85], 0
	v_mov_b64_e32 v[86:87], 0
	v_mov_b64_e32 v[88:89], 0
	v_mov_b64_e32 v[90:91], 0
	v_mov_b64_e32 v[92:93], 0
	v_mov_b64_e32 v[94:95], 0
	v_mov_b64_e32 v[96:97], 0
	v_mov_b64_e32 v[98:99], 0
	v_mov_b64_e32 v[100:101], 0
	v_mov_b64_e32 v[102:103], 0
	v_mov_b64_e32 v[104:105], 0
	v_mov_b64_e32 v[106:107], 0
	v_mov_b64_e32 v[108:109], 0
	v_mov_b64_e32 v[110:111], 0
	v_mov_b64_e32 v[112:113], 0
	v_mov_b64_e32 v[114:115], 0
	v_mov_b64_e32 v[116:117], 0
	v_mov_b64_e32 v[118:119], 0
	v_mov_b64_e32 v[120:121], 0
	v_mov_b64_e32 v[122:123], 0
	v_mov_b64_e32 v[124:125], 0
	v_mov_b64_e32 v[126:127], 0

; template <int NT, class Epi>
; __device__ __forceinline__ void gemm_phase(LAS unsigned char* lds, const int K, const Sched& S, const Epi& E, const int wave_s) {
;     ...
;         const bool has_next = S.next(ui + 1, nxt);
;         const char* nA = has_next ? S.a_base(nxt) : cA; const char* nB = has_next ? S.b_base(nxt) : cB;
;         constexpr int nt = NT;
;         for (int t = 0; t < nt; t += 2) {
;             const bool last = (t == nt - 2);
;             asm volatile(".p2align 4" ::: "memory");
;             const char* a1 = cA + (size_t)(t + 1) * kstep;
;             const char* a2 = last ? nA : cA + (size_t)(t + 2) * kstep; const char* b2 = last ? nB : cB + (size_t)(t + 2) * kstep;
;             const char* a3 = a2 + kstep; const char* b3 = b2 + kstep;
;             PG8_LDB(B0, 0, 0); PG8_LDB(B1, 0, 1); PG8_SCHED; PG8_LDA(At, 0, 0); PG8_STAGE(PG8_SA(1, 1), a1 + hstep, voffA);
;             PG8_WAIT_V(8); PG8_WAIT_L(0); PG8_BAR; PG8_MMA(0, 0, At, B0); PG8_MMA(0, 1, At, B1); PG8_BAR; PG8_SCHED;
;             PG8_LDA(At, 0, 1); PG8_STAGE(PG8_SB(0, 0), b2, voffB); PG8_STAGE(PG8_SB(0, 1), b2 + hstep, voffB); PG8_STAGE(PG8_SA(0, 0), a2, voffA);
;             PG8_WAIT_V(8); PG8_WAIT_L(0); PG8_BAR; PG8_MMA(1, 0, At, B0); PG8_MMA(1, 1, At, B1); PG8_BAR; PG8_SCHED;
;             PG8_LDB(B0, 1, 0); PG8_LDB(B1, 1, 1); PG8_SCHED; PG8_LDA(At, 1, 0); PG8_STAGE(PG8_SA(0, 1), a2 + hstep, voffA);
;             PG8_WAIT_V(8); PG8_WAIT_L(0); PG8_BAR; PG8_MMA(0, 0, At, B0); PG8_MMA(0, 1, At, B1); PG8_BAR; PG8_SCHED;
;             PG8_LDA(At, 1, 1); PG8_STAGE(PG8_SB(1, 0), b3, voffB); PG8_STAGE(PG8_SB(1, 1), b3 + hstep, voffB); PG8_STAGE(PG8_SA(1, 0), a3, voffA);
;             PG8_WAIT_V(8); PG8_WAIT_L(0); PG8_BAR; PG8_MMA(1, 0, At, B0); PG8_MMA(1, 1, At, B1); PG8_BAR; PG8_SCHED;
;         }
;         if (wr == 0) PG8_BAR;
;         const bool keep = E(acc, cur, wr, wc, fr, fq);
;         __builtin_amdgcn_s_waitcnt(0x0F70);
;         if (!has_next) break;
;         if (!keep) {
; #pragma unroll
;             for (int a = 0; a < 2; ++a)
; #pragma unroll
;                 for (int b = 0; b < 2; ++b)
; #pragma unroll
;                     for (int m = 0; m < 4; ++m)
; #pragma unroll
;                         for (int n = 0; n < 2; ++n) acc[a][b][m][n] = (f32x4){0.f, 0.f, 0.f, 0.f};
;         }
;         cur = nxt; cA = nA; cB = nB; ++ui;
.LBB0_90:
	s_ashr_i32 s13, s12, 31
	s_lshl_b64 s[14:15], s[12:13], 20
	s_add_u32 s24, s46, s14
	s_addc_u32 s25, s47, s15
	s_and_b64 s[14:15], s[38:39], exec
	s_cselect_b32 s13, s25, s31
	s_cselect_b32 s19, s24, s30
	s_ashr_i32 s11, s10, 31
	s_lshl_b64 s[14:15], s[10:11], 20
	s_add_u32 s26, s20, s14
	s_addc_u32 s27, s21, s15
	s_and_b64 s[14:15], s[38:39], exec
	s_cselect_b32 s11, s27, s41
	s_cselect_b32 s91, s26, s40
	s_add_u32 s30, s30, 0x80080
	s_addc_u32 s31, s31, 0
	s_add_u32 s96, s40, 0x100
	v_mov_b32_e32 v0, 0
	s_addc_u32 s97, s41, 0
	s_mov_b32 vcc_lo, -2
	v_mov_b64_e32 v[0:1], 0
	v_mov_b64_e32 v[2:3], 0
	v_mov_b64_e32 v[4:5], 0
	v_mov_b64_e32 v[6:7], 0
	v_mov_b64_e32 v[8:9], 0
	v_mov_b64_e32 v[10:11], 0
	v_mov_b64_e32 v[12:13], 0
	v_mov_b64_e32 v[14:15], 0
	v_mov_b64_e32 v[16:17], 0
	v_mov_b64_e32 v[18:19], 0
	v_mov_b64_e32 v[20:21], 0
	v_mov_b64_e32 v[22:23], 0
	v_mov_b64_e32 v[24:25], 0
	v_mov_b64_e32 v[26:27], 0
	v_mov_b64_e32 v[28:29], 0
	v_mov_b64_e32 v[30:31], 0
	v_mov_b64_e32 v[32:33], 0
	v_mov_b64_e32 v[34:35], 0
	v_mov_b64_e32 v[36:37], 0
	v_mov_b64_e32 v[38:39], 0
	v_mov_b64_e32 v[40:41], 0
	v_mov_b64_e32 v[42:43], 0
	v_mov_b64_e32 v[44:45], 0
	v_mov_b64_e32 v[46:47], 0
	v_mov_b64_e32 v[48:49], 0
	v_mov_b64_e32 v[50:51], 0
	v_mov_b64_e32 v[52:53], 0
	v_mov_b64_e32 v[54:55], 0
	v_mov_b64_e32 v[56:57], 0
	v_mov_b64_e32 v[58:59], 0
	v_mov_b64_e32 v[60:61], 0
	v_mov_b64_e32 v[62:63], 0
	v_mov_b64_e32 v[64:65], 0
	v_mov_b64_e32 v[66:67], 0
	v_mov_b64_e32 v[68:69], 0
	v_mov_b64_e32 v[70:71], 0
	v_mov_b64_e32 v[72:73], 0
	v_mov_b64_e32 v[74:75], 0
	v_mov_b64_e32 v[76:77], 0
	v_mov_b64_e32 v[78:79], 0
	v_mov_b64_e32 v[80:81], 0
	v_mov_b64_e32 v[82:83], 0
	v_mov_b64_e32 v[84:85], 0
	v_mov_b64_e32 v[86:87], 0
	v_mov_b64_e32 v[88:89], 0
	v_mov_b64_e32 v[90:91], 0
	v_mov_b64_e32 v[92:93], 0
	v_mov_b64_e32 v[94:95], 0
	v_mov_b64_e32 v[96:97], 0
	v_mov_b64_e32 v[98:99], 0
	v_mov_b64_e32 v[100:101], 0
	v_mov_b64_e32 v[102:103], 0
	v_mov_b64_e32 v[104:105], 0
	v_mov_b64_e32 v[106:107], 0
	v_mov_b64_e32 v[108:109], 0
	v_mov_b64_e32 v[110:111], 0
	v_mov_b64_e32 v[112:113], 0
	v_mov_b64_e32 v[114:115], 0
	v_mov_b64_e32 v[116:117], 0
	v_mov_b64_e32 v[118:119], 0
	v_mov_b64_e32 v[120:121], 0
	v_mov_b64_e32 v[122:123], 0
	v_mov_b64_e32 v[124:125], 0
	v_mov_b64_e32 v[126:127], 0

; template <int NT, class Epi>
; __device__ __forceinline__ void gemm_phase(LAS unsigned char* lds, const int K, const Sched& S, const Epi& E, const int wave_s) {
;     ...
;         const bool has_next = S.next(ui + 1, nxt);
;         const char* nA = has_next ? S.a_base(nxt) : cA; const char* nB = has_next ? S.b_base(nxt) : cB;
;         constexpr int nt = NT;
;         for (int t = 0; t < nt; t += 2) {
;             const bool last = (t == nt - 2);
;             asm volatile(".p2align 4" ::: "memory");
;             const char* a1 = cA + (size_t)(t + 1) * kstep;
;             const char* a2 = last ? nA : cA + (size_t)(t + 2) * kstep; const char* b2 = last ? nB : cB + (size_t)(t + 2) * kstep;
;             const char* a3 = a2 + kstep; const char* b3 = b2 + kstep;
;             PG8_LDB(B0, 0, 0); PG8_LDB(B1, 0, 1); PG8_SCHED; PG8_LDA(At, 0, 0); PG8_STAGE(PG8_SA(1, 1), a1 + hstep, voffA);
;             PG8_WAIT_V(8); PG8_WAIT_L(0); PG8_BAR; PG8_MMA(0, 0, At, B0); PG8_MMA(0, 1, At, B1); PG8_BAR; PG8_SCHED;
;             PG8_LDA(At, 0, 1); PG8_STAGE(PG8_SB(0, 0), b2, voffB); PG8_STAGE(PG8_SB(0, 1), b2 + hstep, voffB); PG8_STAGE(PG8_SA(0, 0), a2, voffA);
;             PG8_WAIT_V(8); PG8_WAIT_L(0); PG8_BAR; PG8_MMA(1, 0, At, B0); PG8_MMA(1, 1, At, B1); PG8_BAR; PG8_SCHED;
;             PG8_LDB(B0, 1, 0); PG8_LDB(B1, 1, 1); PG8_SCHED; PG8_LDA(At, 1, 0); PG8_STAGE(PG8_SA(0, 1), a2 + hstep, voffA);
;             PG8_WAIT_V(8); PG8_WAIT_L(0); PG8_BAR; PG8_MMA(0, 0, At, B0); PG8_MMA(0, 1, At, B1); PG8_BAR; PG8_SCHED;
;             PG8_LDA(At, 1, 1); PG8_STAGE(PG8_SB(1, 0), b3, voffB); PG8_STAGE(PG8_SB(1, 1), b3 + hstep, voffB); PG8_STAGE(PG8_SA(1, 0), a3, voffA);
;             PG8_WAIT_V(8); PG8_WAIT_L(0); PG8_BAR; PG8_MMA(1, 0, At, B0); PG8_MMA(1, 1, At, B1); PG8_BAR; PG8_SCHED;
;         }
;         if (wr == 0) PG8_BAR;
;         const bool keep = E(acc, cur, wr, wc, fr, fq);
;         __builtin_amdgcn_s_waitcnt(0x0F70);
;         if (!has_next) break;
;         if (!keep) {
; #pragma unroll
;             for (int a = 0; a < 2; ++a)
; #pragma unroll
;                 for (int b = 0; b < 2; ++b)
; #pragma unroll
;                     for (int m = 0; m < 4; ++m)
; #pragma unroll
;                         for (int n = 0; n < 2; ++n) acc[a][b][m][n] = (f32x4){0.f, 0.f, 0.f, 0.f};
;         }
;         cur = nxt; cA = nA; cB = nB; ++ui;
.LBB0_116:
	s_ashr_i32 s19, s18, 31
	s_lshl_b64 s[14:15], s[18:19], 20
	s_add_u32 s24, s80, s14
	s_addc_u32 s25, s81, s15
	s_and_b64 s[14:15], s[38:39], exec
	s_cselect_b32 s19, s25, s29
	s_cselect_b32 s87, s24, s28
	s_ashr_i32 s13, s12, 31
	s_lshl_b64 s[14:15], s[12:13], 20
	s_add_u32 s26, s37, s14
	s_addc_u32 s27, s88, s15
	s_and_b64 s[14:15], s[38:39], exec
	s_cselect_b32 s13, s27, s31
	s_cselect_b32 s90, s26, s30
	s_add_u32 s28, s28, 0x80080
	s_addc_u32 s29, s29, 0
	s_add_u32 s91, s30, 0x100
	v_mov_b32_e32 v0, 0
	s_addc_u32 s96, s31, 0
	s_mov_b32 s97, -2
	v_mov_b64_e32 v[0:1], 0
	v_mov_b64_e32 v[2:3], 0
	v_mov_b64_e32 v[4:5], 0
	v_mov_b64_e32 v[6:7], 0
	v_mov_b64_e32 v[8:9], 0
	v_mov_b64_e32 v[10:11], 0
	v_mov_b64_e32 v[12:13], 0
	v_mov_b64_e32 v[14:15], 0
	v_mov_b64_e32 v[16:17], 0
	v_mov_b64_e32 v[18:19], 0
	v_mov_b64_e32 v[20:21], 0
	v_mov_b64_e32 v[22:23], 0
	v_mov_b64_e32 v[24:25], 0
	v_mov_b64_e32 v[26:27], 0
	v_mov_b64_e32 v[28:29], 0
	v_mov_b64_e32 v[30:31], 0
	v_mov_b64_e32 v[32:33], 0
	v_mov_b64_e32 v[34:35], 0
	v_mov_b64_e32 v[36:37], 0
	v_mov_b64_e32 v[38:39], 0
	v_mov_b64_e32 v[40:41], 0
	v_mov_b64_e32 v[42:43], 0
	v_mov_b64_e32 v[44:45], 0
	v_mov_b64_e32 v[46:47], 0
	v_mov_b64_e32 v[48:49], 0
	v_mov_b64_e32 v[50:51], 0
	v_mov_b64_e32 v[52:53], 0
	v_mov_b64_e32 v[54:55], 0
	v_mov_b64_e32 v[56:57], 0
	v_mov_b64_e32 v[58:59], 0
	v_mov_b64_e32 v[60:61], 0
	v_mov_b64_e32 v[62:63], 0
	v_mov_b64_e32 v[64:65], 0
	v_mov_b64_e32 v[66:67], 0
	v_mov_b64_e32 v[68:69], 0
	v_mov_b64_e32 v[70:71], 0
	v_mov_b64_e32 v[72:73], 0
	v_mov_b64_e32 v[74:75], 0
	v_mov_b64_e32 v[76:77], 0
	v_mov_b64_e32 v[78:79], 0
	v_mov_b64_e32 v[80:81], 0
	v_mov_b64_e32 v[82:83], 0
	v_mov_b64_e32 v[84:85], 0
	v_mov_b64_e32 v[86:87], 0
	v_mov_b64_e32 v[88:89], 0
	v_mov_b64_e32 v[90:91], 0
	v_mov_b64_e32 v[92:93], 0
	v_mov_b64_e32 v[94:95], 0
	v_mov_b64_e32 v[96:97], 0
	v_mov_b64_e32 v[98:99], 0
	v_mov_b64_e32 v[100:101], 0
	v_mov_b64_e32 v[102:103], 0
	v_mov_b64_e32 v[104:105], 0
	v_mov_b64_e32 v[106:107], 0
	v_mov_b64_e32 v[108:109], 0
	v_mov_b64_e32 v[110:111], 0
	v_mov_b64_e32 v[112:113], 0
	v_mov_b64_e32 v[114:115], 0
	v_mov_b64_e32 v[116:117], 0
	v_mov_b64_e32 v[118:119], 0
	v_mov_b64_e32 v[120:121], 0
	v_mov_b64_e32 v[122:123], 0
	v_mov_b64_e32 v[124:125], 0
	v_mov_b64_e32 v[126:127], 0

; template <int NT, class Epi>
; __device__ __forceinline__ void gemm_phase(LAS unsigned char* lds, const int K, const Sched& S, const Epi& E, const int wave_s) {
;     ...
;         const bool has_next = S.next(ui + 1, nxt);
;         const char* nA = has_next ? S.a_base(nxt) : cA; const char* nB = has_next ? S.b_base(nxt) : cB;
;         constexpr int nt = NT;
;         for (int t = 0; t < nt; t += 2) {
;             const bool last = (t == nt - 2);
;             asm volatile(".p2align 4" ::: "memory");
;             const char* a1 = cA + (size_t)(t + 1) * kstep;
;             const char* a2 = last ? nA : cA + (size_t)(t + 2) * kstep; const char* b2 = last ? nB : cB + (size_t)(t + 2) * kstep;
;             const char* a3 = a2 + kstep; const char* b3 = b2 + kstep;
;             PG8_LDB(B0, 0, 0); PG8_LDB(B1, 0, 1); PG8_SCHED; PG8_LDA(At, 0, 0); PG8_STAGE(PG8_SA(1, 1), a1 + hstep, voffA);
;             PG8_WAIT_V(8); PG8_WAIT_L(0); PG8_BAR; PG8_MMA(0, 0, At, B0); PG8_MMA(0, 1, At, B1); PG8_BAR; PG8_SCHED;
;             PG8_LDA(At, 0, 1); PG8_STAGE(PG8_SB(0, 0), b2, voffB); PG8_STAGE(PG8_SB(0, 1), b2 + hstep, voffB); PG8_STAGE(PG8_SA(0, 0), a2, voffA);
;             PG8_WAIT_V(8); PG8_WAIT_L(0); PG8_BAR; PG8_MMA(1, 0, At, B0); PG8_MMA(1, 1, At, B1); PG8_BAR; PG8_SCHED;
;             PG8_LDB(B0, 1, 0); PG8_LDB(B1, 1, 1); PG8_SCHED; PG8_LDA(At, 1, 0); PG8_STAGE(PG8_SA(0, 1), a2 + hstep, voffA);
;             PG8_WAIT_V(8); PG8_WAIT_L(0); PG8_BAR; PG8_MMA(0, 0, At, B0); PG8_MMA(0, 1, At, B1); PG8_BAR; PG8_SCHED;
;             PG8_LDA(At, 1, 1); PG8_STAGE(PG8_SB(1, 0), b3, voffB); PG8_STAGE(PG8_SB(1, 1), b3 + hstep, voffB); PG8_STAGE(PG8_SA(1, 0), a3, voffA);
;             PG8_WAIT_V(8); PG8_WAIT_L(0); PG8_BAR; PG8_MMA(1, 0, At, B0); PG8_MMA(1, 1, At, B1); PG8_BAR; PG8_SCHED;
;         }
;         if (wr == 0) PG8_BAR;
;         const bool keep = E(acc, cur, wr, wc, fr, fq);
;         __builtin_amdgcn_s_waitcnt(0x0F70);
;         if (!has_next) break;
;         if (!keep) {
; #pragma unroll
;             for (int a = 0; a < 2; ++a)
; #pragma unroll
;                 for (int b = 0; b < 2; ++b)
; #pragma unroll
;                     for (int m = 0; m < 4; ++m)
; #pragma unroll
;                         for (int n = 0; n < 2; ++n) acc[a][b][m][n] = (f32x4){0.f, 0.f, 0.f, 0.f};
;         }
;         cur = nxt; cA = nA; cB = nB; ++ui;
.LBB0_190:
	s_ashr_i32 s31, s30, 31
	s_lshl_b64 s[14:15], s[30:31], 20
	s_add_u32 s9, s80, s14
	s_addc_u32 s14, s81, s15
	s_add_u32 s38, s9, s40
	s_addc_u32 s39, s14, s41
	s_and_b64 s[14:15], s[26:27], exec
	s_cselect_b32 s9, s39, s43
	s_cselect_b32 s25, s38, s42
	s_ashr_i32 s29, s28, 31
	s_lshl_b64 s[14:15], s[28:29], 20
	s_add_u32 s14, s37, s14
	s_addc_u32 s15, s88, s15
	s_add_u32 s40, s14, s40
	s_addc_u32 s41, s15, s41
	s_and_b64 s[14:15], s[26:27], exec
	s_cselect_b32 s29, s41, s45
	s_cselect_b32 s31, s40, s44
	s_add_u32 s42, s42, 0x80080
	s_addc_u32 s43, s43, 0
	s_add_u32 s34, s44, 0x100
	v_mov_b32_e32 v0, 0
	s_addc_u32 s35, s45, 0
	s_mov_b32 vcc_lo, -2
	v_mov_b64_e32 v[0:1], 0
	v_mov_b64_e32 v[2:3], 0
	v_mov_b64_e32 v[4:5], 0
	v_mov_b64_e32 v[6:7], 0
	v_mov_b64_e32 v[8:9], 0
	v_mov_b64_e32 v[10:11], 0
	v_mov_b64_e32 v[12:13], 0
	v_mov_b64_e32 v[14:15], 0
	v_mov_b64_e32 v[16:17], 0
	v_mov_b64_e32 v[18:19], 0
	v_mov_b64_e32 v[20:21], 0
	v_mov_b64_e32 v[22:23], 0
	v_mov_b64_e32 v[24:25], 0
	v_mov_b64_e32 v[26:27], 0
	v_mov_b64_e32 v[28:29], 0
	v_mov_b64_e32 v[30:31], 0
	v_mov_b64_e32 v[32:33], 0
	v_mov_b64_e32 v[34:35], 0
	v_mov_b64_e32 v[36:37], 0
	v_mov_b64_e32 v[38:39], 0
	v_mov_b64_e32 v[40:41], 0
	v_mov_b64_e32 v[42:43], 0
	v_mov_b64_e32 v[44:45], 0
	v_mov_b64_e32 v[46:47], 0
	v_mov_b64_e32 v[48:49], 0
	v_mov_b64_e32 v[50:51], 0
	v_mov_b64_e32 v[52:53], 0
	v_mov_b64_e32 v[54:55], 0
	v_mov_b64_e32 v[56:57], 0
	v_mov_b64_e32 v[58:59], 0
	v_mov_b64_e32 v[60:61], 0
	v_mov_b64_e32 v[62:63], 0
	v_mov_b64_e32 v[64:65], 0
	v_mov_b64_e32 v[66:67], 0
	v_mov_b64_e32 v[68:69], 0
	v_mov_b64_e32 v[70:71], 0
	v_mov_b64_e32 v[72:73], 0
	v_mov_b64_e32 v[74:75], 0
	v_mov_b64_e32 v[76:77], 0
	v_mov_b64_e32 v[78:79], 0
	v_mov_b64_e32 v[80:81], 0
	v_mov_b64_e32 v[82:83], 0
	v_mov_b64_e32 v[84:85], 0
	v_mov_b64_e32 v[86:87], 0
	v_mov_b64_e32 v[88:89], 0
	v_mov_b64_e32 v[90:91], 0
	v_mov_b64_e32 v[92:93], 0
	v_mov_b64_e32 v[94:95], 0
	v_mov_b64_e32 v[96:97], 0
	v_mov_b64_e32 v[98:99], 0
	v_mov_b64_e32 v[100:101], 0
	v_mov_b64_e32 v[102:103], 0
	v_mov_b64_e32 v[104:105], 0
	v_mov_b64_e32 v[106:107], 0
	v_mov_b64_e32 v[108:109], 0
	v_mov_b64_e32 v[110:111], 0
	v_mov_b64_e32 v[112:113], 0
	v_mov_b64_e32 v[114:115], 0
	v_mov_b64_e32 v[116:117], 0
	v_mov_b64_e32 v[118:119], 0
	v_mov_b64_e32 v[120:121], 0
	v_mov_b64_e32 v[122:123], 0
	v_mov_b64_e32 v[124:125], 0
	v_mov_b64_e32 v[126:127], 0

;     __device__ __forceinline__ const char* a_base(const Unit& u) const { return ((u.src == 1 || u.src == 5) ? A1 : A0) + (size_t)u.pm * tstep + u.koff; }
;     __device__ __forceinline__ const char* b_base(const Unit& u) const { return ((u.src == 1 || u.src == 5) ? B1 : B0) + (size_t)u.pn * tstep + u.koff; }
; #define PG8_STAGE(bufoff, gbase, voff) do { _Pragma("unroll") for (int _i = 0; _i < 2; ++_i) \
;         __builtin_amdgcn_global_load_lds((const unsigned*)((const char*)(gbase) + (voff)[_i]), (LAS unsigned*)(lds + (bufoff) + ldsw + _i * 8192), 16, 0, 0); } while (0)
; #define PG8_WAIT_V(n) asm volatile("s_waitcnt vmcnt(" #n ")" ::: "memory")
; #define PG8_BAR __builtin_amdgcn_s_barrier()
; template <int NT, class Epi>
; __device__ __forceinline__ void gemm_phase(LAS unsigned char* lds, const int K, const Sched& S, const Epi& E, const int wave_s) {
;     ...
;     f32x4 acc[2][2][4][2];
; #pragma unroll
;     for (int a = 0; a < 2; ++a)
; #pragma unroll
;         for (int b = 0; b < 2; ++b)
; #pragma unroll
;             for (int m = 0; m < 4; ++m)
; #pragma unroll
;                 for (int n = 0; n < 2; ++n) acc[a][b][m][n] = (f32x4){0.f, 0.f, 0.f, 0.f};
;     bf16x8 At[4][2], B0[2][2], B1[2][2];
;     const char* cA = S.a_base(cur); const char* cB = S.b_base(cur);
;     PG8_STAGE(PG8_SB(0, 0), cB, voffB); PG8_STAGE(PG8_SB(0, 1), cB + hstep, voffB); PG8_STAGE(PG8_SA(0, 0), cA, voffA); PG8_STAGE(PG8_SA(0, 1), cA + hstep, voffA);
;     if (wr == 1) PG8_BAR;
;     PG8_WAIT_V(2); PG8_BAR;
;     PG8_STAGE(PG8_SB(1, 0), cB + kstep, voffB); PG8_STAGE(PG8_SA(1, 0), cA + kstep, voffA); PG8_STAGE(PG8_SB(1, 1), cB + hstep + kstep, voffB);
;     PG8_WAIT_V(6); PG8_BAR;
.LBB0_209:
	v_lshrrev_b32_e32 v16, 1, v11
	v_and_b32_e32 v16, 24, v16
	v_and_b32_e32 v15, 15, v11
	v_lshlrev_b32_e32 v17, 1, v16
	v_lshlrev_b32_e32 v11, 2, v11
	v_lshl_or_b32 v168, s25, 6, v15
	v_lshl_or_b32 v15, v15, 6, v17
	s_lshl_b32 s9, s25, 13
	v_and_b32_e32 v11, 32, v11
	v_bitop3_b32 v17, v15, s9, v11 bitop3:0xde
	s_lshl_b32 s9, s24, 5
	s_and_b32 s9, s9, 0x60
	s_lshl_b32 s14, s9, 7
	v_readlane_b32 s17, v254, 58
	v_bitop3_b32 v11, v15, s14, v11 bitop3:0xde
	s_add_i32 s14, s17, s21
	v_lshl_add_u64 v[6:7], v[6:7], 0, s[50:51]
	s_mov_b32 m0, s14
	s_waitcnt vmcnt(2)
	s_barrier
	global_load_lds_dwordx4 v[6:7], off
	v_lshl_add_u64 v[4:5], v[4:5], 0, s[50:51]
	s_add_i32 m0, s14, 0x2000
	s_add_i32 s87, s11, 0x8000
	s_add_i32 s90, s11, 0xa000
	global_load_lds_dwordx4 v[4:5], off
	v_lshl_add_u64 v[0:1], v[0:1], 0, s[50:51]
	s_mov_b32 m0, s87
	s_add_u32 s14, s18, 0x80080
	v_readlane_b32 s22, v254, 59
	global_load_lds_dwordx4 v[0:1], off
	v_lshl_add_u64 v[0:1], v[2:3], 0, s[50:51]
	s_mov_b32 m0, s90
	s_addc_u32 s15, s19, 0
	s_add_i32 s21, s22, s21
	global_load_lds_dwordx4 v[0:1], off
	v_lshl_add_u64 v[0:1], s[14:15], 0, v[176:177]
	s_mov_b32 m0, s21
	s_mov_b32 s1, s5
	global_load_lds_dwordx4 v[0:1], off
	v_lshl_add_u64 v[0:1], s[14:15], 0, v[140:141]
	s_add_i32 m0, s21, 0x2000
	s_add_i32 s14, 0, 0x10000
	global_load_lds_dwordx4 v[0:1], off
	v_lshlrev_b32_e32 v0, 15, v13
	v_and_b32_e32 v0, 0xffff0000, v0
	v_lshl_add_u32 v0, v12, 12, v0
	v_and_b32_e32 v1, 1, v13
	v_add_u32_e32 v170, s14, v11
	s_add_i32 s14, 0, 0x14000
	v_lshl_or_b32 v0, v1, 6, v0
	v_add_u32_e32 v171, s14, v11
	s_add_i32 s14, 0, 0x4000
	v_lshl_add_u32 v146, v14, 1, v0
	v_lshlrev_b32_e32 v0, 15, v8
	v_add_u32_e32 v172, s14, v17
	s_add_i32 s14, 0, 0x8000
	v_and_b32_e32 v0, 0xffff0000, v0
	v_add_u32_e32 v175, s14, v17
	s_add_i32 s14, 0, 0xc000
	v_lshl_add_u32 v0, v9, 12, v0
	v_and_b32_e32 v1, 1, v8
	s_waitcnt vmcnt(6)
	v_add_u32_e32 v187, s14, v17
	v_lshl_or_b32 v0, v1, 6, v0
	s_mov_b32 s14, s16
	s_cmpk_lt_u32 s20, 0x100
	v_lshl_add_u32 v148, v10, 1, v0
	v_mov_b32_e32 v0, 0
	v_writelane_b32 v254, s14, 28
	v_add_u32_e32 v169, 0, v17
	v_add_u32_e32 v173, s17, v11
	v_add_u32_e32 v174, s22, v11
	s_cselect_b64 s[26:27], -1, 0
	v_or_b32_e32 v190, s9, v16
	v_mov_b32_e32 v147, v177
	v_mov_b32_e32 v149, v177
	s_mov_b32 s91, 0
	v_writelane_b32 v254, s15, 29
	s_mov_b32 s9, s16
	v_mov_b64_e32 v[0:1], 0
	v_mov_b64_e32 v[2:3], 0
	v_mov_b64_e32 v[4:5], 0
	v_mov_b64_e32 v[6:7], 0
	v_mov_b64_e32 v[8:9], 0
	v_mov_b64_e32 v[10:11], 0
	v_mov_b64_e32 v[12:13], 0
	v_mov_b64_e32 v[14:15], 0
	v_mov_b64_e32 v[16:17], 0
	v_mov_b64_e32 v[18:19], 0
	v_mov_b64_e32 v[20:21], 0
	v_mov_b64_e32 v[22:23], 0
	v_mov_b64_e32 v[24:25], 0
	v_mov_b64_e32 v[26:27], 0
	v_mov_b64_e32 v[28:29], 0
	v_mov_b64_e32 v[30:31], 0
	v_mov_b64_e32 v[32:33], 0
	v_mov_b64_e32 v[34:35], 0
	v_mov_b64_e32 v[36:37], 0
	v_mov_b64_e32 v[38:39], 0
	v_mov_b64_e32 v[40:41], 0
	v_mov_b64_e32 v[42:43], 0
	v_mov_b64_e32 v[44:45], 0
	v_mov_b64_e32 v[46:47], 0
	v_mov_b64_e32 v[48:49], 0
	v_mov_b64_e32 v[50:51], 0
	v_mov_b64_e32 v[52:53], 0
	v_mov_b64_e32 v[54:55], 0
	v_mov_b64_e32 v[56:57], 0
	v_mov_b64_e32 v[58:59], 0
	v_mov_b64_e32 v[60:61], 0
	v_mov_b64_e32 v[62:63], 0
	v_mov_b64_e32 v[64:65], 0
	v_mov_b64_e32 v[66:67], 0
	v_mov_b64_e32 v[68:69], 0
	v_mov_b64_e32 v[70:71], 0
	v_mov_b64_e32 v[72:73], 0
	v_mov_b64_e32 v[74:75], 0
	v_mov_b64_e32 v[76:77], 0
	v_mov_b64_e32 v[78:79], 0
	v_mov_b64_e32 v[80:81], 0
	v_mov_b64_e32 v[82:83], 0
	v_mov_b64_e32 v[84:85], 0
	v_mov_b64_e32 v[86:87], 0
	v_mov_b64_e32 v[88:89], 0
	v_mov_b64_e32 v[90:91], 0
	v_mov_b64_e32 v[92:93], 0
	v_mov_b64_e32 v[94:95], 0
	v_mov_b64_e32 v[96:97], 0
	v_mov_b64_e32 v[98:99], 0
	v_mov_b64_e32 v[100:101], 0
	v_mov_b64_e32 v[102:103], 0
	v_mov_b64_e32 v[104:105], 0
	v_mov_b64_e32 v[106:107], 0
	v_mov_b64_e32 v[108:109], 0
	v_mov_b64_e32 v[110:111], 0
	v_mov_b64_e32 v[112:113], 0
	v_mov_b64_e32 v[114:115], 0
	v_mov_b64_e32 v[116:117], 0
	v_mov_b64_e32 v[118:119], 0
	v_mov_b64_e32 v[120:121], 0
	v_mov_b64_e32 v[122:123], 0
	v_mov_b64_e32 v[124:125], 0
	v_mov_b64_e32 v[126:127], 0
	v_readlane_b32 s21, v252, 41
	s_barrier
	s_branch .LBB0_212

; template <int NT, class Epi>
; __device__ __forceinline__ void gemm_phase(LAS unsigned char* lds, const int K, const Sched& S, const Epi& E, const int wave_s) {
;     ...
;         const bool keep = E(acc, cur, wr, wc, fr, fq);
;         __builtin_amdgcn_s_waitcnt(0x0F70);
;         if (!has_next) break;
;         if (!keep) {
; #pragma unroll
;             for (int a = 0; a < 2; ++a)
; #pragma unroll
;                 for (int b = 0; b < 2; ++b)
; #pragma unroll
;                     for (int m = 0; m < 4; ++m)
; #pragma unroll
;                         for (int n = 0; n < 2; ++n) acc[a][b][m][n] = (f32x4){0.f, 0.f, 0.f, 0.f};
;         }
;         cur = nxt; cA = nA; cB = nB; ++ui;
.LBB0_327:
	s_and_b64 vcc, exec, s[38:39]
	s_mov_b64 s[8:9], -1
	s_mov_b64 s[38:39], 0x800
	s_cbranch_vccnz .LBB0_211
	s_andn2_b64 vcc, exec, s[12:13]
	s_cbranch_vccnz .LBB0_330
	v_mov_b32_e32 v0, 0
	v_mov_b64_e32 v[0:1], 0
	v_mov_b64_e32 v[2:3], 0
	v_mov_b64_e32 v[4:5], 0
	v_mov_b64_e32 v[6:7], 0
	v_mov_b64_e32 v[8:9], 0
	v_mov_b64_e32 v[10:11], 0
	v_mov_b64_e32 v[12:13], 0
	v_mov_b64_e32 v[14:15], 0
	v_mov_b64_e32 v[16:17], 0
	v_mov_b64_e32 v[18:19], 0
	v_mov_b64_e32 v[20:21], 0
	v_mov_b64_e32 v[22:23], 0
	v_mov_b64_e32 v[24:25], 0
	v_mov_b64_e32 v[26:27], 0
	v_mov_b64_e32 v[28:29], 0
	v_mov_b64_e32 v[30:31], 0
	v_mov_b64_e32 v[32:33], 0
	v_mov_b64_e32 v[34:35], 0
	v_mov_b64_e32 v[36:37], 0
	v_mov_b64_e32 v[38:39], 0
	v_mov_b64_e32 v[40:41], 0
	v_mov_b64_e32 v[42:43], 0
	v_mov_b64_e32 v[44:45], 0
	v_mov_b64_e32 v[46:47], 0
	v_mov_b64_e32 v[48:49], 0
	v_mov_b64_e32 v[50:51], 0
	v_mov_b64_e32 v[52:53], 0
	v_mov_b64_e32 v[54:55], 0
	v_mov_b64_e32 v[56:57], 0
	v_mov_b64_e32 v[58:59], 0
	v_mov_b64_e32 v[60:61], 0
	v_mov_b64_e32 v[62:63], 0
	v_mov_b64_e32 v[64:65], 0
	v_mov_b64_e32 v[66:67], 0
	v_mov_b64_e32 v[68:69], 0
	v_mov_b64_e32 v[70:71], 0
	v_mov_b64_e32 v[72:73], 0
	v_mov_b64_e32 v[74:75], 0
	v_mov_b64_e32 v[76:77], 0
	v_mov_b64_e32 v[78:79], 0
	v_mov_b64_e32 v[80:81], 0
	v_mov_b64_e32 v[82:83], 0
	v_mov_b64_e32 v[84:85], 0
	v_mov_b64_e32 v[86:87], 0
	v_mov_b64_e32 v[88:89], 0
	v_mov_b64_e32 v[90:91], 0
	v_mov_b64_e32 v[92:93], 0
	v_mov_b64_e32 v[94:95], 0
	v_mov_b64_e32 v[96:97], 0
	v_mov_b64_e32 v[98:99], 0
	v_mov_b64_e32 v[100:101], 0
	v_mov_b64_e32 v[102:103], 0
	v_mov_b64_e32 v[104:105], 0
	v_mov_b64_e32 v[106:107], 0
	v_mov_b64_e32 v[108:109], 0
	v_mov_b64_e32 v[110:111], 0
	v_mov_b64_e32 v[112:113], 0
	v_mov_b64_e32 v[114:115], 0
	v_mov_b64_e32 v[116:117], 0
	v_mov_b64_e32 v[118:119], 0
	v_mov_b64_e32 v[120:121], 0
	v_mov_b64_e32 v[122:123], 0
	v_mov_b64_e32 v[124:125], 0
	v_mov_b64_e32 v[126:127], 0
